# E6: pool_seam help-mode claims without re-reading the global counter first (one global round trip less per claim round); on top of E1+E2
# speedup vs baseline: 1.0129x; 1.0075x over previous
.LBB0_22:
	v_mov_b32_e32 v2, s72
	ds_read_b32 v2, v2
	s_waitcnt lgkmcnt(0)
	v_cmp_lt_u32_e32 vcc, s18, v2
	v_mov_b32_e32 v2, -1
	s_cbranch_vccnz .LBB0_28
	s_mov_b64 s[6:7], exec
	v_mbcnt_lo_u32_b32 v2, s6, 0
	v_mbcnt_hi_u32_b32 v2, s7, v2
	v_cmp_eq_u32_e32 vcc, 0, v2
	s_and_saveexec_b64 s[4:5], vcc
	s_cbranch_execz .LBB0_26
	s_bcnt1_i32_b64 s2, s[6:7]
	s_lshl_b32 s2, s2, 3
	v_mov_b32_e32 v3, s2
	global_atomic_add v3, v67, v3, s[24:25] sc0

.LBB0_317:
	v_readlane_b32 s2, v252, 24
	s_nop 1
	v_mov_b32_e32 v2, s2
	ds_read_b32 v2, v2
	s_waitcnt lgkmcnt(0)
	v_cmp_le_u32_e32 vcc, s24, v2
	v_mov_b32_e32 v2, -1
	s_cbranch_vccnz .LBB0_323
	s_mov_b64 s[18:19], exec
	v_mbcnt_lo_u32_b32 v2, s18, 0
	v_mbcnt_hi_u32_b32 v2, s19, v2
	v_cmp_eq_u32_e32 vcc, 0, v2
	s_and_saveexec_b64 s[8:9], vcc
	s_cbranch_execz .LBB0_321
	s_bcnt1_i32_b64 s2, s[18:19]
	s_lshl_b32 s2, s2, 3
	v_mov_b32_e32 v3, s2
	global_atomic_add v3, v147, v3, s[34:35] sc0

.LBB0_2465:
	v_readlane_b32 s2, v252, 24
	s_nop 1
	v_mov_b32_e32 v2, s2
	ds_read_b32 v2, v2
	s_waitcnt lgkmcnt(0)
	v_cmp_le_u32_e32 vcc, s15, v2
	v_mov_b32_e32 v2, -1
	s_cbranch_vccnz .LBB0_2471
	s_mov_b64 s[18:19], exec
	v_mbcnt_lo_u32_b32 v2, s18, 0
	v_mbcnt_hi_u32_b32 v2, s19, v2
	v_cmp_eq_u32_e32 vcc, 0, v2
	s_and_saveexec_b64 s[8:9], vcc
	s_cbranch_execz .LBB0_2469
	s_bcnt1_i32_b64 s2, s[18:19]
	s_lshl_b32 s2, s2, 3
	v_mov_b32_e32 v3, s2
	global_atomic_add v3, v147, v3, s[34:35] sc0
